# combined LRU reductions + nt hint on the LRU flush stores
# baseline (speedup 1.0000x reference)
; #define LAS __attribute__((address_space(3)))
; #define LDS_BARRIER() do { asm volatile("s_waitcnt lgkmcnt(0)" ::: "memory"); __builtin_amdgcn_s_barrier(); asm volatile("" ::: "memory"); } while (0)
; template <int dir>
; __device__ __forceinline__ void lru_pass(LAS unsigned char* lds, const Params& P, int b, int h, int q, bool dry) {
;     ...
;             LDS_BARRIER();
;             if (sc >= 2) {
;                 if (dir == 0) {
; #pragma unroll
;                     for (int i = 0; i < 4; ++i) { const int id = tid + i * NTHREADS; *(u32x4*)(Hg + (size_t)(t0_prev + (id >> 3)) * DM + (id & 7) * 4) = *(const LAS u32x4*)(TOUT + (id >> 3) * IO_WP + (id & 7) * 16); }
;                 } else if (!dry) {
; #pragma unroll
;                     for (int i = 0; i < 2; ++i) { const int id = tid + i * NTHREADS; *(u32x4*)(Z + ZSLAB(8 + h, (size_t)b * SEQ + t0_prev + (id >> 2)) + q * 32 + (id & 3) * 8) = *(const LAS u32x4*)(TOUT + (id >> 2) * IO_NP + (id & 3) * 16); }
;                 }
;             }
.LBB0_295:
	s_waitcnt lgkmcnt(0)
	s_barrier
	s_setprio 0
	s_cmp_lt_u32 s93, 2
	s_cbranch_scc1 .LBB0_297
	s_add_u32 s18, s80, 0x5fe0000
	s_addc_u32 s19, s81, 0
	ds_read_b128 v[32:35], v158
	ds_read_b128 v[36:39], v159
	v_lshl_add_u64 v[48:49], v[134:135], 0, s[18:19]
	v_lshl_add_u64 v[50:51], v[132:133], 0, s[18:19]
	s_waitcnt lgkmcnt(1)
	global_store_dwordx4 v[48:49], v[32:35], off nt
	s_waitcnt lgkmcnt(0)
	global_store_dwordx4 v[50:51], v[36:39], off nt

; #define LAS __attribute__((address_space(3)))
; #define LDS_BARRIER() do { asm volatile("s_waitcnt lgkmcnt(0)" ::: "memory"); __builtin_amdgcn_s_barrier(); asm volatile("" ::: "memory"); } while (0)
; template <int dir>
; __device__ __forceinline__ void lru_pass(LAS unsigned char* lds, const Params& P, int b, int h, int q, bool dry) {
;     ...
;     {
; #pragma unroll
;         for (int i = 0; i < 2; ++i) { const int idx = tid + i * NTHREADS, gate = idx >> 9, n = (idx >> 4) & 31, kc = idx & 15;
;             *(LAS u32x4*)(WB + (gate * 32 + n) * XC_PITCH + kc * 16) = *(const u32x4*)(LruW + ((size_t)((dir * 2 + gate) * 8 + h) * 128 + q * 32 + n) * 128 + kc * 8); }
;         const float br = -LOG2E * P.lru_ba[(dir * 8 + h) * 128 + chl], bi = -LOG2E * P.lru_bx[(dir * 8 + h) * 128 + chl];
;         const float lam = P.lru_lambda[dir * 1024 + ch];
;         const float cl = -8.0f * LOG2E * log1pf(__expf(-lam));
;     ...
;         LDS_BARRIER();
;         if (dir == 0) {
; #pragma unroll
;             for (int i = 0; i < 4; ++i) { const int id = tid + i * NTHREADS; *(u32x4*)(Hg + (size_t)(t0_prev + (id >> 3)) * DM + (id & 7) * 4) = *(const LAS u32x4*)(TOUT + (id >> 3) * IO_WP + (id & 7) * 16); }
;         } else if (!dry) {
; #pragma unroll
;             for (int i = 0; i < 2; ++i) { const int id = tid + i * NTHREADS; *(u32x4*)(Z + ZSLAB(8 + h, (size_t)b * SEQ + t0_prev + (id >> 2)) + q * 32 + (id & 3) * 8) = *(const LAS u32x4*)(TOUT + (id >> 2) * IO_NP + (id & 3) * 16); }
;         }
.Lpp_f_noy:
	s_waitcnt lgkmcnt(0)
	s_barrier
	s_add_u32 s18, s80, 0x5fe0000
	s_addc_u32 s19, s81, 0
	ds_read_b128 v[0:3], v158
	ds_read_b128 v[4:7], v159
	v_lshl_add_u64 v[8:9], v[134:135], 0, s[18:19]
	v_lshl_add_u64 v[10:11], v[132:133], 0, s[18:19]
	s_waitcnt lgkmcnt(1)
	global_store_dwordx4 v[8:9], v[0:3], off nt
	s_waitcnt lgkmcnt(0)
	global_store_dwordx4 v[10:11], v[4:7], off nt
	s_waitcnt lgkmcnt(0)
	s_add_u32 s42, s22, 0x1b00000
	s_addc_u32 s43, s23, 0
	v_mov_b32_e32 v32, v167
	s_barrier
	s_or_b32 s0, s26, 16
	v_and_b32_e32 v15, 31, v32
	v_or_b32_e32 v17, s28, v15
	v_add_u32_e32 v13, 0x200, v32
	v_or_b32_e32 v8, s27, v17
	v_ashrrev_i32_e32 v11, 9, v32
	v_ashrrev_i32_e32 v14, 9, v13
	v_lshlrev_b32_e32 v8, 2, v8
	v_mov_b32_e32 v9, v65
	v_lshl_add_u32 v2, v11, 3, s0
	v_lshl_add_u32 v6, v14, 3, s0
	v_lshl_add_u64 v[8:9], s[64:65], 0, v[8:9]
	s_movk_i32 s0, 0x1000
	v_add_co_u32_e32 v8, vcc, s0, v8
	v_and_b32_e32 v12, 15, v32
	s_nop 0
	v_addc_co_u32_e32 v9, vcc, 0, v9, vcc
	global_load_dword v16, v[8:9], off
	v_bfe_u32 v10, v32, 4, 5
	v_lshlrev_b32_e32 v64, 4, v12
	v_ashrrev_i32_e32 v3, 31, v2
	v_ashrrev_i32_e32 v7, 31, v6
	v_or_b32_e32 v4, s28, v10
	v_lshl_add_u64 v[0:1], s[38:39], 0, v[64:65]
	v_lshlrev_b64 v[2:3], 15, v[2:3]
	v_lshlrev_b64 v[6:7], 15, v[6:7]
	v_lshlrev_b32_e32 v4, 8, v4
	v_mov_b32_e32 v5, v65
	v_lshl_add_u64 v[2:3], v[0:1], 0, v[2:3]
	v_lshl_add_u64 v[0:1], v[0:1], 0, v[6:7]
	v_lshl_add_u64 v[2:3], v[2:3], 0, v[4:5]
	v_lshl_add_u64 v[4:5], v[0:1], 0, v[4:5]
	global_load_dwordx4 v[0:3], v[2:3], off
	s_nop 0
	global_load_dwordx4 v[4:7], v[4:5], off
	v_lshrrev_b32_e32 v8, 1, v32
	v_lshlrev_b32_e32 v9, 2, v32
	v_and_b32_e32 v20, 12, v8
	v_lshl_or_b32 v11, v11, 5, v10
	v_add_u32_e32 v8, s88, v64
	v_lshl_or_b32 v14, v14, 5, v10
	v_mad_u64_u32 v[10:11], s[6:7], v11, s89, v[8:9]
	s_or_b32 s8, s26, 8
	v_and_or_b32 v20, v9, 16, v20
	v_lshlrev_b32_e32 v21, 2, v17
	v_mad_u64_u32 v[8:9], s[6:7], v14, s89, v[8:9]
	v_lshl_or_b32 v9, s8, 9, v21
	global_load_dword v14, v9, s[58:59]
	s_nop 0
	global_load_dword v9, v9, s[62:63]
	s_mov_b32 s80, 0x3f2aaaab
	s_mov_b32 s81, 0x3f317218
	s_mov_b32 s91, 0x7f800000
	s_mov_b32 s92, 0x33800000
	v_ashrrev_i32_e32 v33, 4, v32
	v_lshlrev_b32_e32 v34, 3, v12
	v_readfirstlane_b32 s4, v32
	s_lshl_b64 s[0:1], s[78:79], 11
	s_lshl_b32 s5, s8, 14
	s_ashr_i32 s6, s4, 6
	s_add_u32 s26, s0, s5
	s_addc_u32 s27, s1, 0
	s_lshl_b32 s0, s28, 1
	v_readlane_b32 s1, v255, 10
	v_and_b32_e32 v19, 3, v32
	s_add_u32 s0, s1, s0
	v_bfe_u32 v18, v32, 5, 1
	v_add_u32_e32 v44, 0, v64
	v_lshlrev_b32_e32 v64, 4, v19
	s_addc_u32 s1, s3, 0
	v_lshl_add_u64 v[136:137], s[0:1], 0, v[64:65]
	s_lshl_b32 s0, s6, 5
	v_lshlrev_b32_e32 v46, 4, v18
	v_or_b32_e32 v37, s0, v46
	v_add_u32_e32 v158, s86, v64
	v_or_b32_e32 v64, 4, v37
	s_movk_i32 s93, 0x880
	v_ashrrev_i32_e32 v36, 3, v32
	v_ashrrev_i32_e32 v38, 3, v13
	v_ashrrev_i32_e32 v140, 2, v32
	v_sub_u32_e32 v39, 0xff, v37
	v_sub_u32_e32 v64, 0xff, v64
	v_lshl_add_u32 v160, v33, 3, -1
	v_mul_lo_u32 v52, v33, s93
	v_lshl_or_b32 v110, v33, 13, v34
	v_mov_b32_e32 v111, v65
	v_lshlrev_b64 v[110:111], 1, v[110:111]
	v_lshl_add_u64 v[108:109], s[48:49], 0, v[110:111]
	global_load_dwordx4 v[68:71], v[108:109], off offset:-2048
	global_load_dwordx4 v[72:75], v[108:109], off
	global_load_dwordx4 v[76:79], v[108:109], off offset:2048
	v_lshl_add_u64 v[108:109], s[50:51], 0, v[110:111]
	global_load_dwordx4 v[80:83], v[108:109], off
	v_lshl_add_u64 v[108:109], s[56:57], 0, v[110:111]
	global_load_dwordx4 v[84:87], v[108:109], off
	v_lshl_add_u64 v[108:109], s[60:61], 0, v[110:111]
	global_load_dwordx4 v[88:91], v[108:109], off
	v_lshl_add_u64 v[108:109], s[66:67], 0, v[110:111]
	global_load_dwordx4 v[92:95], v[108:109], off
	v_lshl_add_u64 v[108:109], s[70:71], 0, v[110:111]
	global_load_dwordx4 v[96:99], v[108:109], off
	v_lshl_add_u64 v[108:109], s[72:73], 0, v[110:111]
	global_load_dwordx4 v[100:103], v[108:109], off
	v_lshl_add_u64 v[108:109], s[74:75], 0, v[110:111]
	global_load_dwordx4 v[104:107], v[108:109], off
	v_lshl_add_u64 v[108:109], s[76:77], 0, v[110:111]
	global_load_dwordx4 v[108:111], v[108:109], off
	s_waitcnt vmcnt(14)
	ds_write_b128 v10, v[0:3]
	s_waitcnt vmcnt(13)
	ds_write_b128 v8, v[4:7]
	v_mul_f32_e32 v11, 0xbfb8aa3b, v16
	v_exp_f32_e32 v11, v11
	v_mul_lo_u32 v57, v39, s89
	v_mul_lo_u32 v58, v39, s30
	v_mul_lo_u32 v114, v64, s89
	v_add_f32_e32 v2, 1.0, v11
	v_add_f32_e32 v3, -1.0, v2
	v_frexp_mant_f32_e32 v4, v2
	v_cvt_f64_f32_e32 v[0:1], v2
	v_sub_f32_e32 v5, v3, v2
	v_frexp_exp_i32_f64_e32 v0, v[0:1]
	v_cmp_gt_f32_e32 vcc, s80, v4
	v_sub_f32_e32 v3, v11, v3
	v_add_f32_e32 v1, 1.0, v5
	v_subbrev_co_u32_e32 v0, vcc, 0, v0, vcc
	v_add_f32_e32 v1, v3, v1
	v_sub_u32_e32 v3, 0, v0
	v_ldexp_f32 v2, v2, v3
	v_ldexp_f32 v1, v1, v3
	v_add_f32_e32 v3, -1.0, v2
	v_add_f32_e32 v4, 1.0, v2
	v_add_f32_e32 v5, 1.0, v3
	v_add_f32_e32 v6, -1.0, v4
	v_sub_f32_e32 v5, v2, v5
	v_sub_f32_e32 v2, v2, v6
	v_add_f32_e32 v5, v1, v5
	v_add_f32_e32 v1, v1, v2
	v_add_f32_e32 v7, v4, v1
	v_rcp_f32_e32 v8, v7
	v_add_f32_e32 v2, v3, v5
	v_sub_f32_e32 v4, v7, v4
	v_sub_f32_e32 v3, v2, v3
	v_sub_f32_e32 v1, v1, v4
	v_mul_f32_e32 v4, v2, v8
	v_sub_f32_e32 v3, v5, v3
	v_mul_f32_e32 v5, v7, v4
	v_fma_f32 v10, v4, v7, -v5
	v_fmac_f32_e32 v10, v4, v1
	v_add_f32_e32 v16, v5, v10
	v_sub_f32_e32 v21, v2, v16
	v_sub_f32_e32 v2, v2, v21
	v_sub_f32_e32 v5, v16, v5
	v_sub_f32_e32 v2, v2, v16
	v_sub_f32_e32 v5, v5, v10
	v_add_f32_e32 v2, v3, v2
	v_add_f32_e32 v2, v5, v2
	v_add_f32_e32 v3, v21, v2
	v_mul_f32_e32 v5, v8, v3
	v_sub_f32_e32 v10, v21, v3
	v_mul_f32_e32 v16, v7, v5
	v_add_f32_e32 v2, v2, v10
; template <int dir>
; __device__ __forceinline__ void lru_pass(LAS unsigned char* lds, const Params& P, int b, int h, int q, bool dry) {
;     ...
;         const float br = -LOG2E * P.lru_ba[(dir * 8 + h) * 128 + chl], bi = -LOG2E * P.lru_bx[(dir * 8 + h) * 128 + chl];
;         const float lam = P.lru_lambda[dir * 1024 + ch];
;         const float cl = -8.0f * LOG2E * log1pf(__expf(-lam));
;     ...
;             unsigned xcb[16], pk[16];
; #pragma unroll
;             for (int v = 0; v < 16; ++v) { const int s = sbase + v; const int tl = dir == 0 ? s : 255 - s; xcb[v] = *(const LAS bf16_t*)(XC + tl * XC_PITCH + chl * 2);
;                 if (dir == 0) pk[v] = *(const LAS bf16_t*)(TIN + tl * IO_NP + nl * 2); else pk[v] = *(const LAS unsigned*)(TIN + tl * IO_WP + nl * 4); }
;             float Pp = 1.f, E = 0.f;
; #pragma unroll
;             for (int v = 0; v < 16; ++v) {
;                 const float xcv = __uint_as_float(xcb[v] << 16);
;                 const float r = __builtin_amdgcn_rcpf(1.0f + __builtin_amdgcn_exp2f(zr[v]));
;                 const float ig = __builtin_amdgcn_rcpf(1.0f + __builtin_amdgcn_exp2f(zi[v]));
;                 const float a = __builtin_amdgcn_exp2f(cl * r);
;                 const float sq = __builtin_amdgcn_sqrtf(fmaf(-a, a, 1.0f));
;                 const float u = sq * ig * xcv;
;                 E = fmaf(a, E, u); Pp *= a; zr[v] = E; zi[v] = Pp; }
;             const float Po = __shfl_xor(Pp, 32), Eo = __shfl_xor(E, 32);
;             const float P0 = g ? Po : Pp, E0 = g ? Eo : E, P1 = g ? Pp : Po, E1 = g ? E : Eo;
;             if (g == 0) { AGG[(wid * 2 + 0) * 32 + nl] = P0 * P1; AGG[(wid * 2 + 1) * 32 + nl] = fmaf(P1, E0, E1); }
;             LDS_BARRIER();
;             float cin = carry, cend = carry;
; #pragma unroll
;             for (int w = 0; w < 8; ++w) { const float pw = AGG[(w * 2 + 0) * 32 + nl], ew = AGG[(w * 2 + 1) * 32 + nl]; if (w == wid) cin = cend; cend = fmaf(pw, cend, ew); }
;             carry = cend;
;             if (g) cin = fmaf(P0, cin, E0);
;             if (!isctx) {
; #pragma unroll
;                 for (int v = 0; v < 16; ++v) { const float hv = fmaf(zi[v], cin, zr[v]);
;                     const int s = sbase + v; const int tl = dir == 0 ? s : 255 - s;
;                     if (dir == 0) *(LAS unsigned*)(TOUT + tl * IO_WP + nl * 4) = (cvt_pk_bf16(hv, 0.f) & 0xffffu) | (pk[v] << 16);
	v_add_f32_e32 v10, v4, v5
	v_fma_f32 v7, v5, v7, -v16
	v_sub_f32_e32 v4, v10, v4
	v_fmac_f32_e32 v7, v5, v1
	v_sub_f32_e32 v1, v5, v4
	v_add_f32_e32 v4, v16, v7
	v_sub_f32_e32 v5, v4, v16
	v_sub_f32_e32 v16, v3, v4
	v_sub_f32_e32 v3, v3, v16
	v_sub_f32_e32 v3, v3, v4
	v_cvt_f32_i32_e32 v0, v0
	v_sub_f32_e32 v5, v5, v7
	v_add_f32_e32 v2, v2, v3
	v_add_f32_e32 v2, v5, v2
	v_add_f32_e32 v2, v16, v2
	v_mul_f32_e32 v2, v8, v2
	v_mul_f32_e32 v6, 0x3f317218, v0
	v_add_f32_e32 v1, v1, v2
	v_add_f32_e32 v2, v10, v1
	v_fma_f32 v5, v0, s81, -v6
	v_fmac_f32_e32 v5, 0xb102e308, v0
	v_sub_f32_e32 v0, v2, v10
	v_mul_f32_e32 v3, v2, v2
	v_sub_f32_e32 v0, v1, v0
	v_add_f32_e32 v1, v6, v5
	v_fmamk_f32 v4, v3, 0x3e9b6dac, v200
	v_sub_f32_e32 v6, v1, v6
	v_fmaak_f32 v4, v3, v4, 0x3f2aaada
	v_sub_f32_e32 v5, v5, v6
	v_ldexp_f32 v6, v2, 1
	v_mul_f32_e32 v2, v2, v3
	v_mul_f32_e32 v2, v2, v4
	v_add_f32_e32 v3, v6, v2
	v_sub_f32_e32 v4, v3, v6
	v_ldexp_f32 v0, v0, 1
	v_sub_f32_e32 v2, v2, v4
	v_add_f32_e32 v0, v0, v2
	v_add_f32_e32 v2, v3, v0
	v_sub_f32_e32 v3, v2, v3
	v_sub_f32_e32 v0, v0, v3
	v_add_f32_e32 v3, v1, v2
	v_sub_f32_e32 v4, v3, v1
	v_sub_f32_e32 v6, v3, v4
	v_sub_f32_e32 v1, v1, v6
	v_sub_f32_e32 v2, v2, v4
	v_add_f32_e32 v1, v2, v1
	v_add_f32_e32 v2, v5, v0
	v_sub_f32_e32 v4, v2, v5
	v_add_f32_e32 v1, v2, v1
	v_sub_f32_e32 v6, v2, v4
	v_add_f32_e32 v2, v3, v1
	v_sub_f32_e32 v5, v5, v6
	v_sub_f32_e32 v0, v0, v4
	v_sub_f32_e32 v3, v2, v3
	v_add_f32_e32 v0, v0, v5
	v_sub_f32_e32 v1, v1, v3
	v_add_f32_e32 v0, v0, v1
	v_add_f32_e32 v0, v2, v0
	v_cmp_neq_f32_e32 vcc, s91, v11
	v_mov_b32_e32 v1, v65
	v_mul_lo_u32 v115, v64, s30
	v_cndmask_b32_e32 v0, v201, v0, vcc
	v_cmp_ngt_f32_e32 vcc, -1.0, v11
	v_mul_lo_u32 v206, v39, s87
	v_mul_lo_u32 v210, v64, s87
	v_cndmask_b32_e32 v0, v202, v0, vcc
	v_cmp_neq_f32_e32 vcc, -1.0, v11
	v_ashrrev_i32_e32 v39, 31, v38
	v_sub_u32_e32 v41, 0xfe, v37
	v_cndmask_b32_e32 v0, v203, v0, vcc
	v_cmp_lt_f32_e64 vcc, |v11|, s92
	v_mul_lo_u32 v59, v41, s89
	v_mul_lo_u32 v60, v41, s30
	v_cndmask_b32_e32 v6, v0, v11, vcc
	v_lshlrev_b32_e32 v2, 4, v32
	v_and_b32_e32 v2, 0x70, v2
	v_lshlrev_b32_e32 v1, 2, v15
	v_add_u32_e32 v45, s95, v2
	v_or3_b32 v2, v19, v20, s0
	s_and_b32 s0, s4, 0x3fffffc0
	v_add_u32_e32 v161, s94, v1
	s_cmp_eq_u32 s6, 7
	v_lshl_add_u32 v254, s0, 2, v161
	s_cselect_b64 s[0:1], -1, 0
	s_cmp_eq_u32 s6, 6
	s_cselect_b64 s[16:17], -1, 0
	s_cmp_eq_u32 s6, 5
	s_cselect_b64 s[4:5], -1, 0
	s_cmp_eq_u32 s6, 4
	s_cselect_b64 s[8:9], -1, 0
	s_cmp_eq_u32 s6, 3
	s_cselect_b64 s[10:11], -1, 0
	s_cmp_eq_u32 s6, 2
	s_cselect_b64 s[12:13], -1, 0
	s_cmp_eq_u32 s6, 1
	s_cselect_b64 s[14:15], -1, 0
	s_lshl_b32 s6, s25, 7
	s_and_b32 s6, s6, 0xe00
	s_lshl_b32 s7, s29, 7
	s_or_b32 s6, s7, s6
	s_add_u32 s6, s6, s44
	v_add_u32_e32 v50, s95, v1
	v_add_u32_e32 v1, 0x400, v32
	s_addc_u32 s7, 0, s45
	v_ashrrev_i32_e32 v40, 3, v1
	v_add_u32_e32 v1, 0x600, v32
	v_and_b32_e32 v32, 7, v32
	s_add_u32 s18, s84, s46
	v_lshlrev_b32_e32 v64, 4, v32
	v_lshl_or_b32 v32, v33, 10, v34
	v_mov_b32_e32 v33, v65
	s_addc_u32 s19, s85, s47
	v_lshl_add_u64 v[144:145], v[32:33], 1, s[18:19]
	v_lshlrev_b64 v[32:33], 12, v[38:39]
	v_lshl_add_u64 v[32:33], s[6:7], 0, v[32:33]
	v_mul_lo_u32 v207, v41, s87
	v_lshl_add_u64 v[32:33], v[32:33], 0, v[64:65]
	v_ashrrev_i32_e32 v41, 31, v40
	v_or_b32_e32 v43, 2, v37
	v_lshl_add_u64 v[252:253], s[42:43], 0, v[32:33]
	v_lshlrev_b64 v[32:33], 12, v[40:41]
	v_ashrrev_i32_e32 v42, 3, v1
	v_sub_u32_e32 v43, 0xff, v43
	v_or_b32_e32 v63, 3, v37
	v_or_b32_e32 v66, 5, v37
	v_or_b32_e32 v67, 6, v37
	v_or_b32_e32 v120, 7, v37
	v_or_b32_e32 v123, 8, v37
	v_or_b32_e32 v126, 9, v37
	v_or_b32_e32 v129, 10, v37
	v_or_b32_e32 v132, 11, v37
	v_or_b32_e32 v135, 12, v37
	v_or_b32_e32 v142, 13, v37
	v_or_b32_e32 v143, 14, v37
	v_or_b32_e32 v37, 15, v37
	v_lshl_add_u64 v[32:33], s[6:7], 0, v[32:33]
	v_mul_lo_u32 v61, v43, s89
	v_mul_lo_u32 v62, v43, s30
	v_sub_u32_e32 v37, 0xff, v37
	v_mul_lo_u32 v208, v43, s87
	v_lshl_add_u64 v[32:33], v[32:33], 0, v[64:65]
	v_ashrrev_i32_e32 v43, 31, v42
	v_sub_u32_e32 v2, 0xff, v2
	v_mul_lo_u32 v204, v37, s89
	v_mul_lo_u32 v205, v37, s30
	v_mul_lo_u32 v221, v37, s87
	v_ashrrev_i32_e32 v37, 31, v36
	v_lshl_add_u64 v[154:155], s[42:43], 0, v[32:33]
	v_lshlrev_b64 v[32:33], 12, v[42:43]
	v_mul_lo_u32 v2, v2, s89
	v_mul_lo_u32 v53, v36, s30
	v_sub_u32_e32 v63, 0xff, v63
	v_sub_u32_e32 v66, 0xff, v66
	v_sub_u32_e32 v67, 0xff, v67
	v_sub_u32_e32 v120, 0xff, v120
	v_sub_u32_e32 v123, 0xff, v123
	v_sub_u32_e32 v126, 0xff, v126
	v_lshlrev_b64 v[36:37], 12, v[36:37]
	v_lshl_add_u64 v[32:33], s[6:7], 0, v[32:33]
	v_lshlrev_b32_e32 v35, 4, v12
	v_add_u32_e32 v47, 0, v2
	v_mov_b32_e32 v2, s88
	v_lshl_add_u32 v49, v17, 1, 0
	v_lshl_add_u32 v51, v15, 1, s86
	v_mul_lo_u32 v112, v63, s89
	v_mul_lo_u32 v113, v63, s30
	v_mul_lo_u32 v116, v66, s89
	v_mul_lo_u32 v117, v66, s30
	v_mul_lo_u32 v118, v67, s89
	v_mul_lo_u32 v119, v67, s30
	v_mul_lo_u32 v121, v120, s89
	v_mul_lo_u32 v122, v120, s30
	v_mul_lo_u32 v124, v123, s89
	v_mul_lo_u32 v125, v123, s30
	v_mul_lo_u32 v127, v126, s89
	v_mul_lo_u32 v128, v126, s30
	v_sub_u32_e32 v129, 0xff, v129
	v_sub_u32_e32 v132, 0xff, v132
	v_sub_u32_e32 v135, 0xff, v135
	v_sub_u32_e32 v142, 0xff, v142
	v_sub_u32_e32 v143, 0xff, v143
	v_mul_lo_u32 v211, v66, s87
	v_mul_lo_u32 v212, v67, s87
	v_mul_lo_u32 v120, v120, s87
	v_mul_lo_u32 v123, v123, s87
	v_mul_lo_u32 v126, v126, s87
	v_lshl_add_u64 v[36:37], s[6:7], 0, v[36:37]
	v_lshl_add_u64 v[32:33], v[32:33], 0, v[64:65]
	v_mov_b32_e32 v66, v65
	v_mov_b32_e32 v67, v65
	s_waitcnt vmcnt(12)
	v_mul_f32_e32 v0, 0xbfb8aa3b, v14
	s_waitcnt vmcnt(11)
; #define LAS __attribute__((address_space(3)))
; template <int dir>
; __device__ __forceinline__ void lru_pass(LAS unsigned char* lds, const Params& P, int b, int h, int q, bool dry) {
;     ...
;         const float cl = -8.0f * LOG2E * log1pf(__expf(-lam));
;     ...
;             f32x16 zr, zi;
; #pragma unroll
;             for (int v = 0; v < 16; ++v) { zr[v] = br; zi[v] = bi; }
;             const int sbase = 32 * wid + 16 * g;
;             { const int sl = 32 * wid + s_i; const int tlA = dir == 0 ? sl : 255 - sl;
;               const LAS unsigned char* ap = XC + tlA * XC_PITCH + 16 * g;
;               const LAS unsigned char* wrp = WB + nl * XC_PITCH + 16 * g; const LAS unsigned char* wip = wrp + 32 * XC_PITCH;
; #pragma unroll
;               for (int ks = 0; ks < 8; ++ks) { const bf16x8 A = *(const LAS bf16x8*)(ap + 32 * ks);
;                   const bf16x8 Br = *(const LAS bf16x8*)(wrp + 32 * ks), Bi = *(const LAS bf16x8*)(wip + 32 * ks);
;                   zr = __builtin_amdgcn_mfma_f32_32x32x16_bf16(A, Br, zr, 0, 0, 0); zi = __builtin_amdgcn_mfma_f32_32x32x16_bf16(A, Bi, zi, 0, 0, 0); } }
;             unsigned xcb[16], pk[16];
; #pragma unroll
;             for (int v = 0; v < 16; ++v) { const int s = sbase + v; const int tl = dir == 0 ? s : 255 - s; xcb[v] = *(const LAS bf16_t*)(XC + tl * XC_PITCH + chl * 2);
;                 if (dir == 0) pk[v] = *(const LAS bf16_t*)(TIN + tl * IO_NP + nl * 2); else pk[v] = *(const LAS unsigned*)(TIN + tl * IO_WP + nl * 4); }
	v_mul_f32_e32 v16, 0xbfb8aa3b, v9
	v_mad_u32_u24 v48, v15, s89, v2
	v_mul_lo_u32 v54, v38, s30
	v_mul_lo_u32 v55, v40, s30
	v_mul_lo_u32 v56, v42, s30
	v_ashrrev_i32_e32 v138, 2, v13
	v_mul_lo_u32 v130, v129, s89
	v_mul_lo_u32 v131, v129, s30
	v_mul_lo_u32 v133, v132, s89
	v_mul_lo_u32 v134, v132, s30
	v_mul_lo_u32 v146, v135, s89
	v_mul_lo_u32 v147, v135, s30
	v_mul_lo_u32 v148, v142, s89
	v_mul_lo_u32 v149, v142, s30
	v_mul_lo_u32 v162, v143, s89
	v_mul_lo_u32 v163, v143, s30
	v_mul_lo_u32 v63, v63, s87
	v_mul_lo_u32 v129, v129, s87
	v_mul_lo_u32 v132, v132, s87
	v_mul_lo_u32 v135, v135, s87
	v_mul_lo_u32 v219, v142, s87
	v_mul_lo_u32 v220, v143, s87
	v_lshl_add_u64 v[36:37], v[36:37], 0, v[64:65]
	v_lshl_add_u64 v[150:151], s[42:43], 0, v[32:33]
	v_mov_b32_e32 v64, v65
	v_add_u32_e32 v32, 0, v35
	v_add_u32_e32 v180, v49, v112
	v_add_u32_e32 v181, v50, v113
	v_add_u32_e32 v182, v49, v114
	v_add_u32_e32 v183, v50, v115
	v_add_u32_e32 v184, v49, v116
	v_add_u32_e32 v185, v50, v117
	v_add_u32_e32 v186, v49, v118
	v_add_u32_e32 v187, v50, v119
	v_add_u32_e32 v188, v49, v121
	v_add_u32_e32 v189, v50, v122
	v_add_u32_e32 v190, v49, v124
	v_add_u32_e32 v191, v50, v125
	v_add_u32_e32 v192, v49, v127
	v_add_u32_e32 v213, v51, v120
	v_add_u32_e32 v214, v51, v123
	v_add_u32_e32 v215, v51, v126
	v_mov_b64_e32 v[114:115], v[66:67]
	v_mov_b64_e32 v[118:119], v[66:67]
	v_mov_b64_e32 v[122:123], v[66:67]
	v_mov_b64_e32 v[126:127], v[66:67]
	s_mov_b32 s78, 0
	v_mov_b32_e32 v156, 0xff800000
	v_mul_f32_e32 v159, 0xc138aa3b, v6
	v_rcp_f32_e32 v159, v159
	s_nop 0
	v_cmp_eq_u32_e32 vcc, 0, v18
	v_mul_lo_u32 v164, v140, s87
	v_ashrrev_i32_e32 v141, 31, v140
	v_mul_lo_u32 v152, v138, s87
	v_ashrrev_i32_e32 v139, 31, v138
	v_mov_b32_e32 v1, v0
	v_mov_b32_e32 v2, v0
	v_mov_b32_e32 v3, v0
	v_mov_b32_e32 v4, v0
	v_mov_b32_e32 v5, v0
	v_mov_b32_e32 v6, v0
	v_mov_b32_e32 v7, v0
	v_mov_b32_e32 v8, v0
	v_mov_b32_e32 v9, v0
	v_mov_b32_e32 v10, v0
	v_mov_b32_e32 v11, v0
	v_mov_b32_e32 v12, v0
	v_mov_b32_e32 v13, v0
	v_mov_b32_e32 v14, v0
	v_mov_b32_e32 v15, v0
	v_mov_b32_e32 v17, v16
	v_mov_b32_e32 v18, v16
	v_mov_b32_e32 v19, v16
	v_mov_b32_e32 v20, v16
	v_mov_b32_e32 v21, v16
	v_mov_b32_e32 v22, v16
	v_mov_b32_e32 v23, v16
	v_mov_b32_e32 v24, v16
	v_mov_b32_e32 v25, v16
	v_mov_b32_e32 v26, v16
	v_mov_b32_e32 v27, v16
	v_mov_b32_e32 v28, v16
	v_mov_b32_e32 v29, v16
	v_mov_b32_e32 v30, v16
	v_mov_b32_e32 v31, v16
	v_lshl_add_u64 v[142:143], s[42:43], 0, v[36:37]
	s_movk_i32 s28, 0x100
	v_mov_b32_e32 v222, 0
	s_mov_b64 s[44:45], 0
	s_movk_i32 s25, 0x700
	v_add_u32_e32 v165, 0x15c00, v32
	v_add_u32_e32 v166, v44, v52
	v_add_u32_e32 v168, v45, v53
	v_add_u32_e32 v169, v45, v54
	v_add_u32_e32 v170, v45, v55
	v_add_u32_e32 v171, v45, v56
	v_add_u32_e32 v172, v47, v46
	v_add_u32_e32 v173, v48, v46
	v_add_u32_e32 v174, v49, v57
	v_add_u32_e32 v175, v50, v58
	v_add_u32_e32 v176, v49, v59
	v_add_u32_e32 v177, v50, v60
	v_add_u32_e32 v178, v49, v61
	v_add_u32_e32 v179, v50, v62
	v_add_u32_e32 v193, v50, v128
	v_add_u32_e32 v194, v49, v130
	v_add_u32_e32 v195, v50, v131
	v_add_u32_e32 v196, v49, v133
	v_add_u32_e32 v197, v50, v134
	v_add_u32_e32 v198, v49, v146
	v_add_u32_e32 v199, v50, v147
	v_add_u32_e32 v200, v49, v148
	v_add_u32_e32 v201, v50, v149
	v_add_u32_e32 v202, v49, v162
	v_add_u32_e32 v203, v50, v163
	v_add_u32_e32 v204, v49, v204
	v_add_u32_e32 v205, v50, v205
	v_add_u32_e32 v206, v51, v206
	v_add_u32_e32 v207, v51, v207
	v_add_u32_e32 v208, v51, v208
	v_add_u32_e32 v209, v51, v63
	v_add_u32_e32 v210, v51, v210
	v_add_u32_e32 v211, v51, v211
	v_add_u32_e32 v212, v51, v212
	v_add_u32_e32 v216, v51, v129
	v_add_u32_e32 v217, v51, v132
	v_add_u32_e32 v218, v51, v135
	v_add_u32_e32 v219, v51, v219
	v_add_u32_e32 v220, v51, v220
	v_add_u32_e32 v221, v51, v221
	v_mov_b64_e32 v[112:113], v[64:65]
	v_mov_b64_e32 v[116:117], v[64:65]
	v_mov_b64_e32 v[120:121], v[64:65]
	v_mov_b64_e32 v[124:125], v[64:65]
	s_mov_b32 s46, 0
	s_mov_b32 s29, 0
	v_lshrrev_b32_e32 v32, 8, v167
	v_mul_u32_u24_e32 v33, 0x3600, v32
	v_add_u32_e32 v168, v168, v33
	v_add_u32_e32 v169, v169, v33
	v_add_u32_e32 v170, v170, v33
	v_add_u32_e32 v171, v171, v33
	v_add_u32_e32 v169, 0xffffee00, v169
	v_add_u32_e32 v170, 0xffffdc00, v170
; #define LAS __attribute__((address_space(3)))
; #define LDS_BARRIER() do { asm volatile("s_waitcnt lgkmcnt(0)" ::: "memory"); __builtin_amdgcn_s_barrier(); asm volatile("" ::: "memory"); } while (0)
; template <int dir>
; __device__ __forceinline__ void lru_pass(LAS unsigned char* lds, const Params& P, int b, int h, int q, bool dry) {
;     ...
;             for (int i = 0; i < NIN; ++i) { const int id = tid + i * NTHREADS;
;                 if (dir == 0) *(LAS u32x4*)(TIN + (id >> 2) * IO_NP + (id & 3) * 16) = inr[i];
;                 else *(LAS u32x4*)(TIN + (id >> 3) * IO_WP + (id & 7) * 16) = inr[i]; }
;             LruTile nxt = cur;
;             if (sc < 8) { nxt = lru_tile(Z, ZC, b, h, dir, sc + 1); lru_load_rows(rows, nxt, tr, cgp);
; #pragma unroll
;                 for (int i = 0; i < NIN; ++i) { const int id = tid + i * NTHREADS;
;                     if (dir == 0) inr[i] = *(const u32x4*)(Zg + (size_t)(nxt.t0 + (id >> 2)) * 128 + (id & 3) * 8);
;                     else inr[i] = *(const u32x4*)(Hg + (size_t)(nxt.t0 + (id >> 3)) * DM + (id & 7) * 4); } }
;             LDS_BARRIER();
;             if (sc >= 2) {
;                 if (dir == 0) {
; #pragma unroll
;                     for (int i = 0; i < 4; ++i) { const int id = tid + i * NTHREADS; *(u32x4*)(Hg + (size_t)(t0_prev + (id >> 3)) * DM + (id & 7) * 4) = *(const LAS u32x4*)(TOUT + (id >> 3) * IO_WP + (id & 7) * 16); }
;                 } else if (!dry) {
; #pragma unroll
;                     for (int i = 0; i < 2; ++i) { const int id = tid + i * NTHREADS; *(u32x4*)(Z + ZSLAB(8 + h, (size_t)b * SEQ + t0_prev + (id >> 2)) + q * 32 + (id & 3) * 8) = *(const LAS u32x4*)(TOUT + (id >> 2) * IO_NP + (id & 3) * 16); }
;                 }
;             }
;             f32x16 zr, zi;
; #pragma unroll
;             for (int v = 0; v < 16; ++v) { zr[v] = br; zi[v] = bi; }
;             const int sbase = 32 * wid + 16 * g;
;             { const int sl = 32 * wid + s_i; const int tlA = dir == 0 ? sl : 255 - sl;
	v_add_u32_e32 v171, 0xffffca00, v171
	v_mul_u32_u24_e32 v66, 0x60000, v32
	v_mov_b32_e32 v67, 0
	v_lshl_add_u64 v[142:143], v[66:67], 0, v[142:143]
	v_lshl_add_u64 v[252:253], v[66:67], 0, v[252:253]
	v_lshl_add_u64 v[154:155], v[66:67], 0, v[154:155]
	v_lshl_add_u64 v[150:151], v[66:67], 0, v[150:151]
	s_mov_b32 s19, -1
	s_mov_b32 s18, 0xfffe0000
	v_lshl_add_u64 v[252:253], v[252:253], 0, s[18:19]
	s_mov_b32 s18, 0xfffc0000
	v_lshl_add_u64 v[154:155], v[154:155], 0, s[18:19]
	s_mov_b32 s18, 0xfffa0000
	v_lshl_add_u64 v[150:151], v[150:151], 0, s[18:19]
	v_mul_u32_u24_e32 v33, 0x1400, v32
	v_add_u32_e32 v164, v164, v33
	v_add_u32_e32 v152, v152, v33
	v_add_u32_e32 v152, 0xffffec00, v152
	v_lshlrev_b32_e32 v33, 6, v32
	v_add_u32_e32 v140, v140, v33
	v_add_u32_e32 v138, v138, v33
	v_add_u32_e32 v138, 0xffffffc0, v138
	v_lshrrev_b32_e32 v33, 6, v167
	s_nop 1
	v_readfirstlane_b32 s18, v33
	s_lshl_b32 s19, s18, 6
	s_sub_i32 s19, s19, 0xe0
	s_mul_i32 s20, s19, 0x110
	v_add_u32_e32 v172, s20, v172
	v_add_u32_e32 v174, s20, v174
	v_add_u32_e32 v176, s20, v176
	v_add_u32_e32 v178, s20, v178
	v_add_u32_e32 v180, s20, v180
	v_add_u32_e32 v182, s20, v182
	v_add_u32_e32 v184, s20, v184
	v_add_u32_e32 v186, s20, v186
	v_add_u32_e32 v188, s20, v188
	v_add_u32_e32 v190, s20, v190
	v_add_u32_e32 v192, s20, v192
	v_add_u32_e32 v194, s20, v194
	v_add_u32_e32 v196, s20, v196
	v_add_u32_e32 v198, s20, v198
	v_add_u32_e32 v200, s20, v200
	v_add_u32_e32 v202, s20, v202
	v_add_u32_e32 v204, s20, v204
	s_mul_i32 s20, s19, 0x90
	v_add_u32_e32 v175, s20, v175
	v_add_u32_e32 v177, s20, v177
	v_add_u32_e32 v179, s20, v179
	v_add_u32_e32 v181, s20, v181
	v_add_u32_e32 v183, s20, v183
	v_add_u32_e32 v185, s20, v185
	v_add_u32_e32 v187, s20, v187
	v_add_u32_e32 v189, s20, v189
	v_add_u32_e32 v191, s20, v191
	v_add_u32_e32 v193, s20, v193
	v_add_u32_e32 v195, s20, v195
	v_add_u32_e32 v197, s20, v197
	v_add_u32_e32 v199, s20, v199
	v_add_u32_e32 v201, s20, v201
	v_add_u32_e32 v203, s20, v203
	v_add_u32_e32 v205, s20, v205
	s_mul_i32 s20, s19, 0x50
	v_add_u32_e32 v206, s20, v206
	v_add_u32_e32 v207, s20, v207
	v_add_u32_e32 v208, s20, v208
	v_add_u32_e32 v209, s20, v209
	v_add_u32_e32 v210, s20, v210
	v_add_u32_e32 v211, s20, v211
	v_add_u32_e32 v212, s20, v212
	v_add_u32_e32 v213, s20, v213
	v_add_u32_e32 v214, s20, v214
	v_add_u32_e32 v215, s20, v215
	v_add_u32_e32 v216, s20, v216
	v_add_u32_e32 v217, s20, v217
	v_add_u32_e32 v218, s20, v218
	v_add_u32_e32 v219, s20, v219
	v_add_u32_e32 v220, s20, v220
	v_add_u32_e32 v221, s20, v221
	s_lshl_b32 s20, s18, 1
	s_sub_i32 s20, 7, s20
	s_lshl_b32 s20, s20, 8
	v_add_u32_e32 v254, s20, v254
	s_sub_i32 s18, 7, s18
	s_lshr_b32 s101, s18, 2
	s_or_b32 s19, s18, 4
	s_cmp_eq_u32 s19, 7
	s_cselect_b64 s[0:1], -1, 0
	s_cmp_eq_u32 s19, 6
	s_cselect_b64 s[16:17], -1, 0
	s_cmp_eq_u32 s19, 5
	s_cselect_b64 s[4:5], -1, 0
	s_cmp_eq_u32 s19, 4
	s_cselect_b64 s[8:9], -1, 0
	s_cmp_eq_u32 s19, 3
	s_cselect_b64 s[10:11], -1, 0
	s_cmp_eq_u32 s19, 2
	s_cselect_b64 s[12:13], -1, 0
	s_cmp_eq_u32 s19, 1
	s_cselect_b64 s[14:15], -1, 0
	s_mov_b32 s98, 0
	s_cmp_eq_u32 s101, 0
	s_cselect_b32 s99, 0x14400, 0
	s_cselect_b32 s100, 0, 0x400
	v_add_u32_e32 v33, 0x14000, v254
	v_mov_b32_e32 v66, 1.0
	v_mov_b32_e32 v67, 0
	ds_write2_b32 v33, v66, v67 offset1:32
	v_lshrrev_b32_e32 v66, 8, v167
	v_lshlrev_b32_e32 v66, 7, v66
	v_bfe_u32 v67, v167, 2, 6
	v_add_u32_e32 v66, v66, v67
	v_and_b32_e32 v67, 3, v167
	v_lshlrev_b32_e32 v67, 4, v67
	v_mul_u32_u24_e32 v168, 0x90, v66
	v_lshl_add_u32 v168, v67, 1, v168
	v_add_u32_e32 v168, s95, v168
	v_add_u32_e32 v169, 0x2400, v168
	v_lshl_add_u32 v66, v66, 8, v67
	v_mov_b32_e32 v67, 0
	s_lshr_b32 s18, s2, 5
	s_add_i32 s18, s18, 8
	s_lshl_b32 s18, s18, 22
	s_add_u32 s18, s18, 0x5470000
	s_and_b32 s19, s2, 7
	s_lshl_b32 s19, s19, 19
	s_add_u32 s18, s18, s19
	s_bfe_u32 s19, s2, 0x20003
	s_lshl_b32 s19, s19, 6
	s_add_u32 s18, s18, s19
	s_add_u32 s18, s22, s18
	s_addc_u32 s19, s23, 0
	v_lshl_add_u64 v[142:143], s[18:19], 0, v[66:67]
	s_mov_b32 s20, 0x4000
	s_mov_b32 s21, 0
	v_lshl_add_u64 v[252:253], v[142:143], 0, s[20:21]
	s_mov_b32 s40, 0x6000000
	s_mov_b32 s41, 0
	s_cmp_eq_u32 s101, 0
	s_cbranch_scc1 .Lpp_b_nox
	s_waitcnt lgkmcnt(0)
	s_barrier
